# k44 variant: K-fragment reads of the keys 0-31 pass fully spread, one extra read after each of the first four MFMAs
# baseline (speedup 1.0000x reference)
; #define SBAR() __builtin_amdgcn_sched_barrier(0)
; template <int OFF> __device__ __forceinline__ bf16x8 k_read(int a) { bf16x8 r; asm volatile("ds_read_b128 %0, %1 offset:%2" : "=&v"(r) : "v"(a), "i"(OFF) : "memory"); return r; }
; __device__ __forceinline__ void partialSM(f32x16& p0, f32x16& p1, float& m_reg, float& mn, float& alpha) {
;   constexpr float C = SCALE * 1.4426950408889634f;
;   float pmax = p0[0];
; #pragma unroll
;   for (int r = 1; r < 16; ++r) pmax = fmaxf(pmax, p0[r]);
; #pragma unroll
;   for (int r = 0; r < 16; ++r) pmax = fmaxf(pmax, p1[r]);
;   { auto rr = __builtin_amdgcn_permlane32_swap(__float_as_uint(pmax), __float_as_uint(pmax), false, false);
;     pmax = fmaxf(__uint_as_float(rr[0]), __uint_as_float(rr[1])); }
;   if (__builtin_expect(__all(pmax - m_reg <= THR / SCALE), 1)) { mn = m_reg; alpha = 1.f; }
;   else { mn = fmaxf(m_reg, pmax); alpha = __builtin_amdgcn_exp2f((m_reg - mn) * C); m_reg = mn; }
; template <int BUFOFF, int D0> __device__ __forceinline__ void qk_step(f32x16& p0, f32x16& p1, int ka0, const bf16x8 (&qr)[8], bf16x8 (&k0)[2], bf16x8 (&k1)[2]) {
;   if constexpr (D0 + 1 < 8) { const int a_ = ka0 ^ ((D0 + 1) << 5); k0[(D0 + 1) & 1] = k_read<BUFOFF>(a_); k1[(D0 + 1) & 1] = k_read<BUFOFF + 8192>(a_); }
;   if constexpr (D0 + 1 < 8) asm volatile("s_waitcnt lgkmcnt(2)" ::: "memory"); else asm volatile("s_waitcnt lgkmcnt(0)" ::: "memory");
;   SBAR();
;   p0 = __builtin_amdgcn_mfma_f32_32x32x16_bf16(k0[D0 & 1], qr[D0], p0, 0, 0, 0);
;   p1 = __builtin_amdgcn_mfma_f32_32x32x16_bf16(k1[D0 & 1], qr[D0], p1, 0, 0, 0);
;   SBAR();
;   if constexpr (D0 + 1 < 8) qk_step<BUFOFF, (D0 + 1 < 8 ? D0 + 1 : 7)>(p0, p1, ka0, qr, k0, k1);
; }
; template <int BUFOFF> __device__ __forceinline__ void qkt_rolling(f32x16& p0, f32x16& p1, int ka0, const bf16x8 (&qr)[8]) {
;   bf16x8 k0[2], k1[2];
;   asm volatile("s_waitcnt lgkmcnt(0)" ::: "memory");
;   k0[0] = k_read<BUFOFF>(ka0); k1[0] = k_read<BUFOFF + 8192>(ka0);
;   qk_step<BUFOFF, 0>(p0, p1, ka0, qr, k0, k1);
; }
.LBB0_430:
	s_setprio 1
	v_lshl_add_u64 v[224:225], v[214:215], 0, s[22:23]
	v_lshl_add_u64 v[228:229], v[216:217], 0, s[22:23]
	s_waitcnt lgkmcnt(0)
	ds_read_b128 v[194:197], v235 offset:0
	ds_read_b128 v[198:201], v236 offset:0
	ds_read_b128 v[202:205], v238 offset:0
	ds_read_b128 v[206:209], v239 offset:0
	v_lshl_add_u64 v[232:233], v[224:225], 0, s[10:11]
	s_add_i32 m0, s62, s25
	s_nop 0
	global_load_lds_dwordx4 v[232:233], off
	v_lshl_add_u64 v[232:233], v[228:229], 0, s[10:11]
	s_add_i32 m0, s62, s66
	s_nop 0
	global_load_lds_dwordx4 v[232:233], off
	s_waitcnt lgkmcnt(3)
	s_nop 0
	v_mfma_f32_32x32x16_bf16 v[146:161], v[194:197], v[162:165], 0
	ds_read_b128 v[194:197], v235 offset:8192
	ds_read_b128 v[130:133], v240 offset:0
	s_waitcnt lgkmcnt(4)
	v_mfma_f32_32x32x16_bf16 v[146:161], v[198:201], v[166:169], v[146:161]
	ds_read_b128 v[198:201], v236 offset:8192
	ds_read_b128 v[134:137], v241 offset:0
	s_waitcnt lgkmcnt(5)
	v_mfma_f32_32x32x16_bf16 v[146:161], v[202:205], v[170:173], v[146:161]
	ds_read_b128 v[202:205], v238 offset:8192
	ds_read_b128 v[138:141], v242 offset:0
	s_waitcnt lgkmcnt(6)
	v_mfma_f32_32x32x16_bf16 v[146:161], v[206:209], v[174:177], v[146:161]
	ds_read_b128 v[206:209], v239 offset:8192
	ds_read_b128 v[142:145], v243 offset:0
	s_waitcnt lgkmcnt(6)
	v_mfma_f32_32x32x16_bf16 v[146:161], v[130:133], v[178:181], v[146:161]
	s_waitcnt lgkmcnt(4)
	v_mfma_f32_32x32x16_bf16 v[146:161], v[134:137], v[182:185], v[146:161]
	s_waitcnt lgkmcnt(2)
	v_mfma_f32_32x32x16_bf16 v[146:161], v[138:141], v[186:189], v[146:161]
	s_waitcnt lgkmcnt(0)
	v_mfma_f32_32x32x16_bf16 v[146:161], v[142:145], v[190:193], v[146:161]
	s_waitcnt lgkmcnt(3)
	v_mfma_f32_32x32x16_bf16 v[130:145], v[194:197], v[162:165], 0
	ds_read_b128 v[194:197], v240 offset:8192
	s_waitcnt lgkmcnt(3)
	v_mfma_f32_32x32x16_bf16 v[130:145], v[198:201], v[166:169], v[130:145]
	ds_read_b128 v[198:201], v241 offset:8192
	s_waitcnt lgkmcnt(3)
	v_mfma_f32_32x32x16_bf16 v[130:145], v[202:205], v[170:173], v[130:145]
	ds_read_b128 v[202:205], v242 offset:8192
	s_waitcnt lgkmcnt(3)
	v_mfma_f32_32x32x16_bf16 v[130:145], v[206:209], v[174:177], v[130:145]
	ds_read_b128 v[206:209], v243 offset:8192
	s_waitcnt lgkmcnt(3)
	v_mfma_f32_32x32x16_bf16 v[130:145], v[194:197], v[178:181], v[130:145]
	s_waitcnt lgkmcnt(2)
	v_mfma_f32_32x32x16_bf16 v[130:145], v[198:201], v[182:185], v[130:145]
	s_waitcnt lgkmcnt(1)
	v_mfma_f32_32x32x16_bf16 v[130:145], v[202:205], v[186:189], v[130:145]
	s_waitcnt lgkmcnt(0)
	v_mfma_f32_32x32x16_bf16 v[130:145], v[206:209], v[190:193], v[130:145]
	s_setprio 0
	v_max3_f32 v0, v146, v147, v148
	v_max3_f32 v194, v154, v155, v156
	v_max3_f32 v0, v0, v149, v150
	v_max3_f32 v194, v194, v157, v158
	v_max3_f32 v0, v0, v151, v152
	v_max3_f32 v194, v194, v159, v160
	v_max_f32_e32 v0, v0, v153
	v_max_f32_e32 v194, v194, v161
	s_nop 4
	v_max3_f32 v196, v130, v131, v132
	v_max3_f32 v197, v138, v139, v140
	v_max3_f32 v196, v196, v133, v134
	v_max3_f32 v197, v197, v141, v142
	v_max3_f32 v196, v196, v135, v136
	v_max3_f32 v197, v197, v143, v144
	v_max_f32_e32 v196, v196, v137
	v_max_f32_e32 v197, v197, v145
	v_max3_f32 v0, v0, v194, v196
	v_max_f32_e32 v0, v0, v197
	v_mov_b32_e32 v194, v0
	s_nop 1
	v_permlane32_swap_b32_e32 v0, v194
	v_max_f32_e32 v0, v0, v194
	v_sub_f32_e32 v194, v0, v246
	v_cmp_ge_f32_e32 vcc, s63, v194
	s_cmp_eq_u64 vcc, exec
	s_cbranch_scc0 .Lda_slow_l0_3
	s_mov_b64 s[6:7], -1
	v_mov_b32_e32 v0, 1.0
	s_branch .LBB0_434

; #define SBAR() __builtin_amdgcn_sched_barrier(0)
; template <int OFF> __device__ __forceinline__ bf16x8 k_read(int a) { bf16x8 r; asm volatile("ds_read_b128 %0, %1 offset:%2" : "=&v"(r) : "v"(a), "i"(OFF) : "memory"); return r; }
; __device__ __forceinline__ void partialSM(f32x16& p0, f32x16& p1, float& m_reg, float& mn, float& alpha) {
;   constexpr float C = SCALE * 1.4426950408889634f;
;   float pmax = p0[0];
; #pragma unroll
;   for (int r = 1; r < 16; ++r) pmax = fmaxf(pmax, p0[r]);
; #pragma unroll
;   for (int r = 0; r < 16; ++r) pmax = fmaxf(pmax, p1[r]);
;   { auto rr = __builtin_amdgcn_permlane32_swap(__float_as_uint(pmax), __float_as_uint(pmax), false, false);
;     pmax = fmaxf(__uint_as_float(rr[0]), __uint_as_float(rr[1])); }
;   if (__builtin_expect(__all(pmax - m_reg <= THR / SCALE), 1)) { mn = m_reg; alpha = 1.f; }
;   else { mn = fmaxf(m_reg, pmax); alpha = __builtin_amdgcn_exp2f((m_reg - mn) * C); m_reg = mn; }
; template <int BUFOFF, int D0> __device__ __forceinline__ void qk_step(f32x16& p0, f32x16& p1, int ka0, const bf16x8 (&qr)[8], bf16x8 (&k0)[2], bf16x8 (&k1)[2]) {
;   if constexpr (D0 + 1 < 8) { const int a_ = ka0 ^ ((D0 + 1) << 5); k0[(D0 + 1) & 1] = k_read<BUFOFF>(a_); k1[(D0 + 1) & 1] = k_read<BUFOFF + 8192>(a_); }
;   if constexpr (D0 + 1 < 8) asm volatile("s_waitcnt lgkmcnt(2)" ::: "memory"); else asm volatile("s_waitcnt lgkmcnt(0)" ::: "memory");
;   SBAR();
;   p0 = __builtin_amdgcn_mfma_f32_32x32x16_bf16(k0[D0 & 1], qr[D0], p0, 0, 0, 0);
;   p1 = __builtin_amdgcn_mfma_f32_32x32x16_bf16(k1[D0 & 1], qr[D0], p1, 0, 0, 0);
;   SBAR();
;   if constexpr (D0 + 1 < 8) qk_step<BUFOFF, (D0 + 1 < 8 ? D0 + 1 : 7)>(p0, p1, ka0, qr, k0, k1);
; }
; template <int BUFOFF> __device__ __forceinline__ void qkt_rolling(f32x16& p0, f32x16& p1, int ka0, const bf16x8 (&qr)[8]) {
;   bf16x8 k0[2], k1[2];
;   asm volatile("s_waitcnt lgkmcnt(0)" ::: "memory");
;   k0[0] = k_read<BUFOFF>(ka0); k1[0] = k_read<BUFOFF + 8192>(ka0);
;   qk_step<BUFOFF, 0>(p0, p1, ka0, qr, k0, k1);
; }
.LBB0_436:
	s_setprio 1
	s_waitcnt lgkmcnt(0)
	ds_read_b128 v[194:197], v235 offset:16384
	ds_read_b128 v[198:201], v236 offset:16384
	ds_read_b128 v[202:205], v238 offset:16384
	ds_read_b128 v[206:209], v239 offset:16384
	v_lshl_add_u64 v[232:233], v[224:225], 0, s[14:15]
	s_mov_b32 m0, s28
	s_nop 0
	global_load_lds_dwordx4 v[232:233], off
	v_lshl_add_u64 v[232:233], v[228:229], 0, s[14:15]
	s_mov_b32 m0, s67
	s_nop 0
	global_load_lds_dwordx4 v[232:233], off
	s_waitcnt lgkmcnt(3)
	s_nop 0
	v_mfma_f32_32x32x16_bf16 v[146:161], v[194:197], v[162:165], 0
	ds_read_b128 v[194:197], v235 offset:24576
	ds_read_b128 v[130:133], v240 offset:16384
	s_waitcnt lgkmcnt(4)
	v_mfma_f32_32x32x16_bf16 v[146:161], v[198:201], v[166:169], v[146:161]
	ds_read_b128 v[198:201], v236 offset:24576
	ds_read_b128 v[134:137], v241 offset:16384
	s_waitcnt lgkmcnt(5)
	v_mfma_f32_32x32x16_bf16 v[146:161], v[202:205], v[170:173], v[146:161]
	ds_read_b128 v[202:205], v238 offset:24576
	ds_read_b128 v[138:141], v242 offset:16384
	s_waitcnt lgkmcnt(6)
	v_mfma_f32_32x32x16_bf16 v[146:161], v[206:209], v[174:177], v[146:161]
	ds_read_b128 v[206:209], v239 offset:24576
	ds_read_b128 v[142:145], v243 offset:16384
	s_waitcnt lgkmcnt(6)
	v_mfma_f32_32x32x16_bf16 v[146:161], v[130:133], v[178:181], v[146:161]
	s_waitcnt lgkmcnt(4)
	v_mfma_f32_32x32x16_bf16 v[146:161], v[134:137], v[182:185], v[146:161]
	s_waitcnt lgkmcnt(2)
	v_mfma_f32_32x32x16_bf16 v[146:161], v[138:141], v[186:189], v[146:161]
	s_waitcnt lgkmcnt(0)
	v_mfma_f32_32x32x16_bf16 v[146:161], v[142:145], v[190:193], v[146:161]
	s_waitcnt lgkmcnt(3)
	v_mfma_f32_32x32x16_bf16 v[130:145], v[194:197], v[162:165], 0
	ds_read_b128 v[194:197], v240 offset:24576
	s_waitcnt lgkmcnt(3)
	v_mfma_f32_32x32x16_bf16 v[130:145], v[198:201], v[166:169], v[130:145]
	ds_read_b128 v[198:201], v241 offset:24576
	s_waitcnt lgkmcnt(3)
	v_mfma_f32_32x32x16_bf16 v[130:145], v[202:205], v[170:173], v[130:145]
	ds_read_b128 v[202:205], v242 offset:24576
	s_waitcnt lgkmcnt(3)
	v_mfma_f32_32x32x16_bf16 v[130:145], v[206:209], v[174:177], v[130:145]
	ds_read_b128 v[206:209], v243 offset:24576
	s_waitcnt lgkmcnt(3)
	v_mfma_f32_32x32x16_bf16 v[130:145], v[194:197], v[178:181], v[130:145]
	s_waitcnt lgkmcnt(2)
	v_mfma_f32_32x32x16_bf16 v[130:145], v[198:201], v[182:185], v[130:145]
	s_waitcnt lgkmcnt(1)
	v_mfma_f32_32x32x16_bf16 v[130:145], v[202:205], v[186:189], v[130:145]
	s_waitcnt lgkmcnt(0)
	v_mfma_f32_32x32x16_bf16 v[130:145], v[206:209], v[190:193], v[130:145]
	s_setprio 0
	v_max3_f32 v194, v146, v147, v148
	v_max3_f32 v195, v154, v155, v156
	v_max3_f32 v194, v194, v149, v150
	v_max3_f32 v195, v195, v157, v158
	v_max3_f32 v194, v194, v151, v152
	v_max3_f32 v195, v195, v159, v160
	v_max_f32_e32 v194, v194, v153
	v_max_f32_e32 v195, v195, v161
	s_nop 4
	v_max3_f32 v196, v130, v131, v132
	v_max3_f32 v197, v138, v139, v140
	v_max3_f32 v196, v196, v133, v134
	v_max3_f32 v197, v197, v141, v142
	v_max3_f32 v196, v196, v135, v136
	v_max3_f32 v197, v197, v143, v144
	v_max_f32_e32 v196, v196, v137
	v_max_f32_e32 v197, v197, v145
	v_max3_f32 v194, v194, v195, v196
	v_max_f32_e32 v194, v194, v197
	v_mov_b32_e32 v195, v194
	s_nop 1
	v_permlane32_swap_b32_e32 v194, v195
	v_max_f32_e32 v194, v194, v195
	v_sub_f32_e32 v195, v194, v246
	v_cmp_ge_f32_e32 vcc, s63, v195
	s_cmp_eq_u64 vcc, exec
	s_cbranch_scc0 .Lda_slow_l0_4
	s_mov_b64 s[6:7], -1
	v_mov_b32_e32 v222, 1.0
	s_branch .LBB0_429

; #define SBAR() __builtin_amdgcn_sched_barrier(0)
; template <int OFF> __device__ __forceinline__ bf16x8 k_read(int a) { bf16x8 r; asm volatile("ds_read_b128 %0, %1 offset:%2" : "=&v"(r) : "v"(a), "i"(OFF) : "memory"); return r; }
; __device__ __forceinline__ void partialSM(f32x16& p0, f32x16& p1, float& m_reg, float& mn, float& alpha) {
;   constexpr float C = SCALE * 1.4426950408889634f;
;   float pmax = p0[0];
; #pragma unroll
;   for (int r = 1; r < 16; ++r) pmax = fmaxf(pmax, p0[r]);
; #pragma unroll
;   for (int r = 0; r < 16; ++r) pmax = fmaxf(pmax, p1[r]);
;   { auto rr = __builtin_amdgcn_permlane32_swap(__float_as_uint(pmax), __float_as_uint(pmax), false, false);
;     pmax = fmaxf(__uint_as_float(rr[0]), __uint_as_float(rr[1])); }
;   if (__builtin_expect(__all(pmax - m_reg <= THR / SCALE), 1)) { mn = m_reg; alpha = 1.f; }
;   else { mn = fmaxf(m_reg, pmax); alpha = __builtin_amdgcn_exp2f((m_reg - mn) * C); m_reg = mn; }
; template <int BUFOFF, int D0> __device__ __forceinline__ void qk_step(f32x16& p0, f32x16& p1, int ka0, const bf16x8 (&qr)[8], bf16x8 (&k0)[2], bf16x8 (&k1)[2]) {
;   if constexpr (D0 + 1 < 8) { const int a_ = ka0 ^ ((D0 + 1) << 5); k0[(D0 + 1) & 1] = k_read<BUFOFF>(a_); k1[(D0 + 1) & 1] = k_read<BUFOFF + 8192>(a_); }
;   if constexpr (D0 + 1 < 8) asm volatile("s_waitcnt lgkmcnt(2)" ::: "memory"); else asm volatile("s_waitcnt lgkmcnt(0)" ::: "memory");
;   SBAR();
;   p0 = __builtin_amdgcn_mfma_f32_32x32x16_bf16(k0[D0 & 1], qr[D0], p0, 0, 0, 0);
;   p1 = __builtin_amdgcn_mfma_f32_32x32x16_bf16(k1[D0 & 1], qr[D0], p1, 0, 0, 0);
;   SBAR();
;   if constexpr (D0 + 1 < 8) qk_step<BUFOFF, (D0 + 1 < 8 ? D0 + 1 : 7)>(p0, p1, ka0, qr, k0, k1);
; }
; template <int BUFOFF> __device__ __forceinline__ void qkt_rolling(f32x16& p0, f32x16& p1, int ka0, const bf16x8 (&qr)[8]) {
;   bf16x8 k0[2], k1[2];
;   asm volatile("s_waitcnt lgkmcnt(0)" ::: "memory");
;   k0[0] = k_read<BUFOFF>(ka0); k1[0] = k_read<BUFOFF + 8192>(ka0);
;   qk_step<BUFOFF, 0>(p0, p1, ka0, qr, k0, k1);
; }
.LBB0_1436:
	s_setprio 1
	v_lshl_add_u64 v[224:225], v[214:215], 0, s[22:23]
	v_lshl_add_u64 v[228:229], v[216:217], 0, s[22:23]
	s_waitcnt lgkmcnt(0)
	ds_read_b128 v[194:197], v235 offset:0
	ds_read_b128 v[198:201], v236 offset:0
	ds_read_b128 v[202:205], v238 offset:0
	ds_read_b128 v[206:209], v239 offset:0
	v_lshl_add_u64 v[232:233], v[224:225], 0, s[10:11]
	s_add_i32 m0, s94, s29
	s_nop 0
	global_load_lds_dwordx4 v[232:233], off
	v_lshl_add_u64 v[232:233], v[228:229], 0, s[10:11]
	s_add_i32 m0, s94, s66
	s_nop 0
	global_load_lds_dwordx4 v[232:233], off
	s_waitcnt lgkmcnt(3)
	s_nop 0
	v_mfma_f32_32x32x16_bf16 v[146:161], v[194:197], v[162:165], 0
	ds_read_b128 v[194:197], v235 offset:8192
	ds_read_b128 v[130:133], v240 offset:0
	s_waitcnt lgkmcnt(4)
	v_mfma_f32_32x32x16_bf16 v[146:161], v[198:201], v[166:169], v[146:161]
	ds_read_b128 v[198:201], v236 offset:8192
	ds_read_b128 v[134:137], v241 offset:0
	s_waitcnt lgkmcnt(5)
	v_mfma_f32_32x32x16_bf16 v[146:161], v[202:205], v[170:173], v[146:161]
	ds_read_b128 v[202:205], v238 offset:8192
	ds_read_b128 v[138:141], v242 offset:0
	s_waitcnt lgkmcnt(6)
	v_mfma_f32_32x32x16_bf16 v[146:161], v[206:209], v[174:177], v[146:161]
	ds_read_b128 v[206:209], v239 offset:8192
	ds_read_b128 v[142:145], v243 offset:0
	s_waitcnt lgkmcnt(6)
	v_mfma_f32_32x32x16_bf16 v[146:161], v[130:133], v[178:181], v[146:161]
	s_waitcnt lgkmcnt(4)
	v_mfma_f32_32x32x16_bf16 v[146:161], v[134:137], v[182:185], v[146:161]
	s_waitcnt lgkmcnt(2)
	v_mfma_f32_32x32x16_bf16 v[146:161], v[138:141], v[186:189], v[146:161]
	s_waitcnt lgkmcnt(0)
	v_mfma_f32_32x32x16_bf16 v[146:161], v[142:145], v[190:193], v[146:161]
	s_waitcnt lgkmcnt(3)
	v_mfma_f32_32x32x16_bf16 v[130:145], v[194:197], v[162:165], 0
	ds_read_b128 v[194:197], v240 offset:8192
	s_waitcnt lgkmcnt(3)
	v_mfma_f32_32x32x16_bf16 v[130:145], v[198:201], v[166:169], v[130:145]
	ds_read_b128 v[198:201], v241 offset:8192
	s_waitcnt lgkmcnt(3)
	v_mfma_f32_32x32x16_bf16 v[130:145], v[202:205], v[170:173], v[130:145]
	ds_read_b128 v[202:205], v242 offset:8192
	s_waitcnt lgkmcnt(3)
	v_mfma_f32_32x32x16_bf16 v[130:145], v[206:209], v[174:177], v[130:145]
	ds_read_b128 v[206:209], v243 offset:8192
	s_waitcnt lgkmcnt(3)
	v_mfma_f32_32x32x16_bf16 v[130:145], v[194:197], v[178:181], v[130:145]
	s_waitcnt lgkmcnt(2)
	v_mfma_f32_32x32x16_bf16 v[130:145], v[198:201], v[182:185], v[130:145]
	s_waitcnt lgkmcnt(1)
	v_mfma_f32_32x32x16_bf16 v[130:145], v[202:205], v[186:189], v[130:145]
	s_waitcnt lgkmcnt(0)
	v_mfma_f32_32x32x16_bf16 v[130:145], v[206:209], v[190:193], v[130:145]
	s_setprio 0
	v_max3_f32 v0, v146, v147, v148
	v_max3_f32 v194, v154, v155, v156
	v_max3_f32 v0, v0, v149, v150
	v_max3_f32 v194, v194, v157, v158
	v_max3_f32 v0, v0, v151, v152
	v_max3_f32 v194, v194, v159, v160
	v_max_f32_e32 v0, v0, v153
	v_max_f32_e32 v194, v194, v161
	s_nop 4
	v_max3_f32 v196, v130, v131, v132
	v_max3_f32 v197, v138, v139, v140
	v_max3_f32 v196, v196, v133, v134
	v_max3_f32 v197, v197, v141, v142
	v_max3_f32 v196, v196, v135, v136
	v_max3_f32 v197, v197, v143, v144
	v_max_f32_e32 v196, v196, v137
	v_max_f32_e32 v197, v197, v145
	v_max3_f32 v0, v0, v194, v196
	v_max_f32_e32 v0, v0, v197
	v_mov_b32_e32 v194, v0
	s_nop 1
	v_permlane32_swap_b32_e32 v0, v194
	v_max_f32_e32 v0, v0, v194
	v_sub_f32_e32 v194, v0, v246
	v_cmp_ge_f32_e32 vcc, s95, v194
	s_cmp_eq_u64 vcc, exec
	s_cbranch_scc0 .Lda_slow_l1_1
	s_mov_b64 s[6:7], -1
	v_mov_b32_e32 v0, 1.0
	s_branch .LBB0_1440

; #define SBAR() __builtin_amdgcn_sched_barrier(0)
; template <int OFF> __device__ __forceinline__ bf16x8 k_read(int a) { bf16x8 r; asm volatile("ds_read_b128 %0, %1 offset:%2" : "=&v"(r) : "v"(a), "i"(OFF) : "memory"); return r; }
; __device__ __forceinline__ void partialSM(f32x16& p0, f32x16& p1, float& m_reg, float& mn, float& alpha) {
;   constexpr float C = SCALE * 1.4426950408889634f;
;   float pmax = p0[0];
; #pragma unroll
;   for (int r = 1; r < 16; ++r) pmax = fmaxf(pmax, p0[r]);
; #pragma unroll
;   for (int r = 0; r < 16; ++r) pmax = fmaxf(pmax, p1[r]);
;   { auto rr = __builtin_amdgcn_permlane32_swap(__float_as_uint(pmax), __float_as_uint(pmax), false, false);
;     pmax = fmaxf(__uint_as_float(rr[0]), __uint_as_float(rr[1])); }
;   if (__builtin_expect(__all(pmax - m_reg <= THR / SCALE), 1)) { mn = m_reg; alpha = 1.f; }
;   else { mn = fmaxf(m_reg, pmax); alpha = __builtin_amdgcn_exp2f((m_reg - mn) * C); m_reg = mn; }
; template <int BUFOFF, int D0> __device__ __forceinline__ void qk_step(f32x16& p0, f32x16& p1, int ka0, const bf16x8 (&qr)[8], bf16x8 (&k0)[2], bf16x8 (&k1)[2]) {
;   if constexpr (D0 + 1 < 8) { const int a_ = ka0 ^ ((D0 + 1) << 5); k0[(D0 + 1) & 1] = k_read<BUFOFF>(a_); k1[(D0 + 1) & 1] = k_read<BUFOFF + 8192>(a_); }
;   if constexpr (D0 + 1 < 8) asm volatile("s_waitcnt lgkmcnt(2)" ::: "memory"); else asm volatile("s_waitcnt lgkmcnt(0)" ::: "memory");
;   SBAR();
;   p0 = __builtin_amdgcn_mfma_f32_32x32x16_bf16(k0[D0 & 1], qr[D0], p0, 0, 0, 0);
;   p1 = __builtin_amdgcn_mfma_f32_32x32x16_bf16(k1[D0 & 1], qr[D0], p1, 0, 0, 0);
;   SBAR();
;   if constexpr (D0 + 1 < 8) qk_step<BUFOFF, (D0 + 1 < 8 ? D0 + 1 : 7)>(p0, p1, ka0, qr, k0, k1);
; }
; template <int BUFOFF> __device__ __forceinline__ void qkt_rolling(f32x16& p0, f32x16& p1, int ka0, const bf16x8 (&qr)[8]) {
;   bf16x8 k0[2], k1[2];
;   asm volatile("s_waitcnt lgkmcnt(0)" ::: "memory");
;   k0[0] = k_read<BUFOFF>(ka0); k1[0] = k_read<BUFOFF + 8192>(ka0);
;   qk_step<BUFOFF, 0>(p0, p1, ka0, qr, k0, k1);
; }
.LBB0_1442:
	s_setprio 1
	s_waitcnt lgkmcnt(0)
	ds_read_b128 v[194:197], v235 offset:16384
	ds_read_b128 v[198:201], v236 offset:16384
	ds_read_b128 v[202:205], v238 offset:16384
	ds_read_b128 v[206:209], v239 offset:16384
	v_lshl_add_u64 v[232:233], v[224:225], 0, s[14:15]
	s_mov_b32 m0, s61
	s_nop 0
	global_load_lds_dwordx4 v[232:233], off
	v_lshl_add_u64 v[232:233], v[228:229], 0, s[14:15]
	s_mov_b32 m0, s67
	s_nop 0
	global_load_lds_dwordx4 v[232:233], off
	s_waitcnt lgkmcnt(3)
	s_nop 0
	v_mfma_f32_32x32x16_bf16 v[146:161], v[194:197], v[162:165], 0
	ds_read_b128 v[194:197], v235 offset:24576
	ds_read_b128 v[130:133], v240 offset:16384
	s_waitcnt lgkmcnt(4)
	v_mfma_f32_32x32x16_bf16 v[146:161], v[198:201], v[166:169], v[146:161]
	ds_read_b128 v[198:201], v236 offset:24576
	ds_read_b128 v[134:137], v241 offset:16384
	s_waitcnt lgkmcnt(5)
	v_mfma_f32_32x32x16_bf16 v[146:161], v[202:205], v[170:173], v[146:161]
	ds_read_b128 v[202:205], v238 offset:24576
	ds_read_b128 v[138:141], v242 offset:16384
	s_waitcnt lgkmcnt(6)
	v_mfma_f32_32x32x16_bf16 v[146:161], v[206:209], v[174:177], v[146:161]
	ds_read_b128 v[206:209], v239 offset:24576
	ds_read_b128 v[142:145], v243 offset:16384
	s_waitcnt lgkmcnt(6)
	v_mfma_f32_32x32x16_bf16 v[146:161], v[130:133], v[178:181], v[146:161]
	s_waitcnt lgkmcnt(4)
	v_mfma_f32_32x32x16_bf16 v[146:161], v[134:137], v[182:185], v[146:161]
	s_waitcnt lgkmcnt(2)
	v_mfma_f32_32x32x16_bf16 v[146:161], v[138:141], v[186:189], v[146:161]
	s_waitcnt lgkmcnt(0)
	v_mfma_f32_32x32x16_bf16 v[146:161], v[142:145], v[190:193], v[146:161]
	s_waitcnt lgkmcnt(3)
	v_mfma_f32_32x32x16_bf16 v[130:145], v[194:197], v[162:165], 0
	ds_read_b128 v[194:197], v240 offset:24576
	s_waitcnt lgkmcnt(3)
	v_mfma_f32_32x32x16_bf16 v[130:145], v[198:201], v[166:169], v[130:145]
	ds_read_b128 v[198:201], v241 offset:24576
	s_waitcnt lgkmcnt(3)
	v_mfma_f32_32x32x16_bf16 v[130:145], v[202:205], v[170:173], v[130:145]
	ds_read_b128 v[202:205], v242 offset:24576
	s_waitcnt lgkmcnt(3)
	v_mfma_f32_32x32x16_bf16 v[130:145], v[206:209], v[174:177], v[130:145]
	ds_read_b128 v[206:209], v243 offset:24576
	s_waitcnt lgkmcnt(3)
	v_mfma_f32_32x32x16_bf16 v[130:145], v[194:197], v[178:181], v[130:145]
	s_waitcnt lgkmcnt(2)
	v_mfma_f32_32x32x16_bf16 v[130:145], v[198:201], v[182:185], v[130:145]
	s_waitcnt lgkmcnt(1)
	v_mfma_f32_32x32x16_bf16 v[130:145], v[202:205], v[186:189], v[130:145]
	s_waitcnt lgkmcnt(0)
	v_mfma_f32_32x32x16_bf16 v[130:145], v[206:209], v[190:193], v[130:145]
	s_setprio 0
	v_max3_f32 v194, v146, v147, v148
	v_max3_f32 v195, v154, v155, v156
	v_max3_f32 v194, v194, v149, v150
	v_max3_f32 v195, v195, v157, v158
	v_max3_f32 v194, v194, v151, v152
	v_max3_f32 v195, v195, v159, v160
	v_max_f32_e32 v194, v194, v153
	v_max_f32_e32 v195, v195, v161
	s_nop 4
	v_max3_f32 v196, v130, v131, v132
	v_max3_f32 v197, v138, v139, v140
	v_max3_f32 v196, v196, v133, v134
	v_max3_f32 v197, v197, v141, v142
	v_max3_f32 v196, v196, v135, v136
	v_max3_f32 v197, v197, v143, v144
	v_max_f32_e32 v196, v196, v137
	v_max_f32_e32 v197, v197, v145
	v_max3_f32 v194, v194, v195, v196
	v_max_f32_e32 v194, v194, v197
	v_mov_b32_e32 v195, v194
	s_nop 1
	v_permlane32_swap_b32_e32 v194, v195
	v_max_f32_e32 v194, v194, v195
	v_sub_f32_e32 v195, v194, v246
	v_cmp_ge_f32_e32 vcc, s95, v195
	s_cmp_eq_u64 vcc, exec
	s_cbranch_scc0 .Lda_slow_l1_2
	s_mov_b64 s[6:7], -1
	v_mov_b32_e32 v222, 1.0
	s_branch .LBB0_1435
